# GEMM2/5 skew grouped by token-tile parity (workgroup id bit 5) instead of feature-tile parity (bit 3): delayed workgroups still share their B tiles in time
# baseline (speedup 1.0000x reference)
.LBB0_623:
	s_cmp_lt_i32 s64, 5
	s_cselect_b64 s[8:9], -1, 0
	s_and_b64 s[0:1], s[8:9], s[0:1]
	s_cmpk_lt_i32 s2, 0x300
	s_cselect_b64 s[6:7], -1, 0
	s_and_b64 s[0:1], s[0:1], s[6:7]
	s_andn2_b64 vcc, exec, s[0:1]
	s_cbranch_vccnz .LBB0_632
	s_and_b32 s0, s62, 7
	s_cmp_lg_u32 s0, 0
	s_cselect_b64 s[0:1], -1, 0
	s_ashr_i32 s18, s62, 3
	s_add_u32 s19, s96, 0x720000
	s_addc_u32 s20, s97, 0
	s_add_u32 s21, s96, 0x13a0000
	s_addc_u32 s22, s97, 0
	s_add_u32 s10, s96, 0x43a0000
	s_addc_u32 s11, s97, 0
	s_add_u32 s23, s96, 0xecc4000
	s_addc_u32 s24, s97, 0
	s_abs_i32 s25, s62
	v_cvt_f32_u32_e32 v2, s25
	v_cndmask_b32_e64 v1, 0, 1, s[0:1]
	s_sub_i32 s0, 0, s25
	s_mov_b64 s[12:13], s[36:37]
	v_rcp_iflag_f32_e32 v2, v2
	v_mbcnt_hi_u32_b32 v89, -1, v213
	s_lshl_b32 s28, s62, 3
	s_mov_b64 s[14:15], s[38:39]
	v_mul_f32_e32 v2, 0x4f7ffffe, v2
	v_cvt_u32_f32_e32 v2, v2
	s_ashr_i32 s26, s62, 31
	s_sub_i32 s27, 0, s62
	s_lshl_b32 s29, s2, 3
	v_readfirstlane_b32 s1, v2
	s_mul_i32 s0, s0, s1
	s_mul_hi_u32 s0, s1, s0
	v_and_b32_e32 v2, 64, v89
	s_sub_i32 s30, 0, s28
	s_add_i32 s31, s1, s0
	v_cmp_ne_u32_e64 s[0:1], 1, v1
	v_mov_b32_e32 v67, 0
	s_movk_i32 s34, 0x90
	s_mov_b32 s35, 0xfffffc0
	s_mov_b32 s36, 0x20000
	s_mov_b32 s37, 0x40000
	s_mov_b32 s38, 0x60000
	s_movk_i32 s39, 0xff00
	s_movk_i32 s40, 0x410
	s_movk_i32 s41, 0x2000
	v_mov_b32_e32 v1, s15
	v_mov_b32_e32 v86, s13
	v_mov_b32_e32 v87, s14
	v_mov_b32_e32 v88, s12
	s_movk_i32 s42, 0x1000
	v_add_u32_e32 v90, 64, v2
	v_xor_b32_e32 v91, 32, v89
	v_xor_b32_e32 v92, 16, v89
	v_xor_b32_e32 v93, 8, v89
	v_xor_b32_e32 v94, 4, v89
	v_xor_b32_e32 v95, 2, v89
	v_xor_b32_e32 v96, 1, v89
	s_bitcmp1_b32 s2, 5
	s_cbranch_scc0 .Lskew_done_g2
	s_memrealtime s[98:99]
	s_waitcnt lgkmcnt(0)
	s_add_u32 s100, s98, 500

.LBB0_877:
	s_cmp_lt_i32 s64, 10
	s_cselect_b64 s[4:5], -1, 0
	s_and_b64 s[0:1], s[4:5], s[0:1]
	s_and_b64 s[0:1], s[0:1], s[6:7]
	s_andn2_b64 vcc, exec, s[0:1]
	s_cbranch_vccnz .LBB0_884
	s_and_b32 s0, s62, 7
	s_cmp_lg_u32 s0, 0
	s_cselect_b64 s[0:1], -1, 0
	s_ashr_i32 s3, s62, 3
	s_add_u32 s8, s96, 0xda0000
	s_addc_u32 s9, s97, 0
	s_add_u32 s10, s96, 0x13a0000
	s_addc_u32 s11, s97, 0
	s_abs_i32 s12, s62
	v_cvt_f32_u32_e32 v1, s12
	v_cndmask_b32_e64 v0, 0, 1, s[0:1]
	s_sub_i32 s0, 0, s12
	s_lshl_b32 s15, s62, 3
	v_rcp_iflag_f32_e32 v1, v1
	s_ashr_i32 s13, s62, 31
	s_sub_i32 s14, 0, s62
	s_lshl_b32 s16, s2, 3
	v_mul_f32_e32 v1, 0x4f7ffffe, v1
	v_cvt_u32_f32_e32 v1, v1
	s_sub_i32 s17, 0, s15
	v_mov_b32_e32 v65, 0
	s_movk_i32 s19, 0x90
	v_readfirstlane_b32 s1, v1
	s_mul_i32 s0, s0, s1
	s_mul_hi_u32 s0, s1, s0
	s_add_i32 s18, s1, s0
	v_cmp_ne_u32_e64 s[0:1], 1, v0
	s_mov_b32 s20, 0xfffffc0
	s_mov_b32 s21, 0x20000
	s_mov_b32 s22, 0x40000
	s_mov_b32 s23, 0x60000
	s_movk_i32 s24, 0xff00
	s_movk_i32 s25, 0x410
	s_movk_i32 s26, 0x2000
	s_bitcmp1_b32 s2, 5
	s_cbranch_scc0 .Lskew_done_g5
	s_memrealtime s[98:99]
	s_waitcnt lgkmcnt(0)
	s_add_u32 s100, s98, 500
